# pull_convert: gain loads (and in one instance the row loads) of a transpose item no longer chained one memory latency at a time; all issued together, counted waits (on split-K v73)
# baseline (speedup 1.0000x reference)
.LBB0_221:
	s_ashr_i32 s4, s8, 31
	s_lshr_b32 s4, s4, 24
	s_add_i32 s4, s8, s4
	s_ashr_i32 s5, s4, 8
	s_and_b32 s4, s4, 0x7ffff00
	s_sub_i32 s4, s8, s4
	s_lshl_b32 s6, s5, 6
	s_lshl_b32 s4, s4, 5
	v_add_u32_e32 v10, s6, v1
	s_ashr_i32 s5, s4, 31
	v_ashrrev_i32_e32 v11, 31, v10
	v_lshl_add_u64 v[18:19], s[4:5], 2, v[6:7]
	v_lshlrev_b64 v[20:21], 15, v[10:11]
	v_lshl_add_u64 v[46:47], v[18:19], 0, v[20:21]
	v_lshl_add_u64 v[10:11], v[10:11], 2, s[18:19]
	global_load_dwordx4 v[18:21], v[46:47], off nt
	s_ashr_i32 s7, s6, 31
	v_add_co_u32_e32 v22, vcc, s22, v46
	s_nop 1
	v_addc_co_u32_e32 v23, vcc, 0, v47, vcc
	global_load_dwordx4 v[22:25], v[22:23], off nt
	v_add_co_u32_e32 v26, vcc, s24, v46
	s_nop 1
	v_addc_co_u32_e32 v27, vcc, 0, v47, vcc
	global_load_dwordx4 v[26:29], v[26:27], off nt
	v_add_co_u32_e32 v30, vcc, s25, v46
	s_nop 1
	v_addc_co_u32_e32 v31, vcc, 0, v47, vcc
	global_load_dwordx4 v[30:33], v[30:31], off nt
	v_add_co_u32_e32 v34, vcc, s29, v46
	s_nop 1
	v_addc_co_u32_e32 v35, vcc, 0, v47, vcc
	global_load_dwordx4 v[34:37], v[34:35], off nt
	v_add_co_u32_e32 v38, vcc, s14, v46
	s_nop 1
	v_addc_co_u32_e32 v39, vcc, 0, v47, vcc
	global_load_dwordx4 v[38:41], v[38:39], off nt
	v_add_co_u32_e32 v42, vcc, s15, v46
	s_nop 1
	v_addc_co_u32_e32 v43, vcc, 0, v47, vcc
	global_load_dwordx4 v[42:45], v[42:43], off nt
	v_add_co_u32_e32 v46, vcc, s28, v46
	s_nop 1
	v_addc_co_u32_e32 v47, vcc, 0, v47, vcc
	global_load_dwordx4 v[46:49], v[46:47], off nt
	global_load_dword v52, v[10:11], off
	global_load_dword v54, v[10:11], off offset:32
	global_load_dword v56, v[10:11], off offset:64
	global_load_dword v58, v[10:11], off offset:96
	global_load_dword v60, v[10:11], off offset:128
	global_load_dword v62, v[10:11], off offset:160
	global_load_dword v64, v[10:11], off offset:192
	global_load_dword v66, v[10:11], off offset:224
	s_waitcnt vmcnt(7)
	v_pk_mul_f32 v[20:21], v[20:21], v[52:53] op_sel_hi:[1,0]
	v_pk_mul_f32 v[18:19], v[18:19], v[52:53] op_sel_hi:[1,0]
	s_waitcnt vmcnt(6)
	v_pk_mul_f32 v[24:25], v[24:25], v[54:55] op_sel_hi:[1,0]
	v_pk_mul_f32 v[22:23], v[22:23], v[54:55] op_sel_hi:[1,0]
	s_waitcnt vmcnt(5)
	v_pk_mul_f32 v[28:29], v[28:29], v[56:57] op_sel_hi:[1,0]
	v_pk_mul_f32 v[26:27], v[26:27], v[56:57] op_sel_hi:[1,0]
	s_waitcnt vmcnt(4)
	v_pk_mul_f32 v[32:33], v[32:33], v[58:59] op_sel_hi:[1,0]
	v_pk_mul_f32 v[30:31], v[30:31], v[58:59] op_sel_hi:[1,0]
	s_waitcnt vmcnt(3)
	v_pk_mul_f32 v[36:37], v[36:37], v[60:61] op_sel_hi:[1,0]
	v_pk_mul_f32 v[34:35], v[34:35], v[60:61] op_sel_hi:[1,0]
	s_waitcnt vmcnt(2)
	v_pk_mul_f32 v[40:41], v[40:41], v[62:63] op_sel_hi:[1,0]
	v_pk_mul_f32 v[38:39], v[38:39], v[62:63] op_sel_hi:[1,0]
	s_waitcnt vmcnt(1)
	v_pk_mul_f32 v[44:45], v[44:45], v[64:65] op_sel_hi:[1,0]
	v_pk_mul_f32 v[42:43], v[42:43], v[64:65] op_sel_hi:[1,0]
	s_waitcnt vmcnt(0)
	v_pk_mul_f32 v[48:49], v[48:49], v[66:67] op_sel_hi:[1,0]
	v_pk_mul_f32 v[10:11], v[46:47], v[66:67] op_sel_hi:[1,0]
	v_add_u32_e32 v46, v12, v13
	ds_write2_b32 v46, v18, v19 offset1:1
	ds_write2_b32 v46, v20, v21 offset0:2 offset1:3
	v_add_u32_e32 v18, 0x420, v46
	ds_write2_b32 v18, v22, v23 offset1:1
	v_add_u32_e32 v18, 0x428, v46
	ds_write2_b32 v18, v24, v25 offset1:1
	v_add_u32_e32 v18, 0x840, v46
	ds_write2_b32 v18, v26, v27 offset1:1
	v_add_u32_e32 v18, 0x848, v46
	ds_write2_b32 v18, v28, v29 offset1:1
	v_add_u32_e32 v18, 0xc60, v46
	ds_write2_b32 v18, v30, v31 offset1:1
	v_add_u32_e32 v18, 0xc68, v46
	ds_write2_b32 v18, v32, v33 offset1:1
	v_add_u32_e32 v18, 0x1080, v46
	ds_write2_b32 v18, v34, v35 offset1:1
	v_add_u32_e32 v18, 0x1088, v46
	ds_write2_b32 v18, v36, v37 offset1:1
	v_add_u32_e32 v18, 0x14a0, v46
	ds_write2_b32 v18, v38, v39 offset1:1
	v_add_u32_e32 v18, 0x14a8, v46
	ds_write2_b32 v18, v40, v41 offset1:1
	v_add_u32_e32 v18, 0x18c0, v46
	ds_write2_b32 v18, v42, v43 offset1:1
	v_add_u32_e32 v18, 0x18c8, v46
	ds_write2_b32 v18, v44, v45 offset1:1
	v_add_u32_e32 v18, 0x1ce0, v46
	ds_write2_b32 v18, v10, v11 offset1:1
	v_add_u32_e32 v10, 0x1ce8, v46
	ds_write2_b32 v10, v48, v49 offset1:1
	s_waitcnt lgkmcnt(0)
	ds_read2_b32 v[22:23], v17 offset0:33 offset1:41
	ds_read2_b32 v[24:25], v17 offset1:8
	ds_read2_b32 v[26:27], v17 offset0:66 offset1:74
	ds_read2_b32 v[28:29], v17 offset0:99 offset1:107
	ds_read2_b32 v[30:31], v17 offset0:132 offset1:140
	ds_read2_b32 v[32:33], v17 offset0:165 offset1:173
	ds_read2_b32 v[34:35], v17 offset0:198 offset1:206
	ds_read2_b32 v[36:37], v17 offset0:231 offset1:239
	s_waitcnt lgkmcnt(7)
	v_bfe_u32 v19, v22, 16, 1
	s_waitcnt lgkmcnt(6)
	v_bfe_u32 v18, v24, 16, 1
	v_add3_u32 v18, v24, v18, s23
	v_lshrrev_b32_e32 v18, 16, v18
	v_add3_u32 v19, v22, v19, s23
	v_and_or_b32 v18, v19, s83, v18
	s_waitcnt lgkmcnt(5)
	v_bfe_u32 v19, v26, 16, 1
	v_add3_u32 v19, v26, v19, s23
	s_waitcnt lgkmcnt(4)
	v_bfe_u32 v20, v28, 16, 1
	v_lshrrev_b32_e32 v19, 16, v19
	v_add3_u32 v20, v28, v20, s23
	v_and_or_b32 v19, v20, s83, v19
	s_waitcnt lgkmcnt(3)
	v_bfe_u32 v20, v30, 16, 1
	v_add3_u32 v20, v30, v20, s23
	s_waitcnt lgkmcnt(2)
	v_bfe_u32 v21, v32, 16, 1
	v_lshrrev_b32_e32 v20, 16, v20
	v_add3_u32 v21, v32, v21, s23
	v_and_or_b32 v20, v21, s83, v20
	s_waitcnt lgkmcnt(1)
	v_bfe_u32 v21, v34, 16, 1
	v_add_u32_e32 v38, s4, v1
	v_add3_u32 v21, v34, v21, s23
	s_waitcnt lgkmcnt(0)
	v_bfe_u32 v22, v36, 16, 1
	v_ashrrev_i32_e32 v39, 31, v38
	v_lshl_add_u64 v[10:11], s[6:7], 1, v[8:9]
	v_lshrrev_b32_e32 v21, 16, v21
	v_add3_u32 v22, v36, v22, s23
	v_lshlrev_b64 v[38:39], 12, v[38:39]
	v_and_or_b32 v21, v22, s83, v21
	v_lshl_add_u64 v[38:39], v[10:11], 0, v[38:39]
	global_store_dwordx4 v[38:39], v[18:21], off nt
	v_bfe_u32 v22, v37, 16, 1
	v_add3_u32 v22, v37, v22, s23
	v_bfe_u32 v18, v25, 16, 1
	v_add3_u32 v18, v25, v18, s23
	v_bfe_u32 v19, v23, 16, 1
	v_lshrrev_b32_e32 v18, 16, v18
	v_add3_u32 v19, v23, v19, s23
	v_and_or_b32 v18, v19, s83, v18
	v_bfe_u32 v19, v27, 16, 1
	v_add3_u32 v19, v27, v19, s23
	v_bfe_u32 v20, v29, 16, 1
	v_lshrrev_b32_e32 v19, 16, v19
	v_add3_u32 v20, v29, v20, s23
	v_and_or_b32 v19, v20, s83, v19
	v_bfe_u32 v20, v31, 16, 1
	v_add3_u32 v20, v31, v20, s23
	v_bfe_u32 v21, v33, 16, 1
	v_lshrrev_b32_e32 v20, 16, v20
	v_add3_u32 v21, v33, v21, s23
	v_and_or_b32 v20, v21, s83, v20
	v_bfe_u32 v21, v35, 16, 1
	v_add3_u32 v21, v35, v21, s23
	v_lshrrev_b32_e32 v21, 16, v21
	v_and_or_b32 v21, v22, s83, v21
	v_add_u32_e32 v22, s4, v14
	v_ashrrev_i32_e32 v23, 31, v22
	v_lshlrev_b64 v[22:23], 12, v[22:23]
	v_lshl_add_u64 v[22:23], v[10:11], 0, v[22:23]
	global_store_dwordx4 v[22:23], v[18:21], off nt
	ds_read2_b32 v[22:23], v17 offset0:49 offset1:57
	ds_read2_b32 v[24:25], v17 offset0:16 offset1:24
	ds_read2_b32 v[26:27], v17 offset0:82 offset1:90
	ds_read2_b32 v[28:29], v17 offset0:115 offset1:123
	ds_read2_b32 v[30:31], v17 offset0:148 offset1:156
	ds_read2_b32 v[32:33], v17 offset0:181 offset1:189
	ds_read2_b32 v[34:35], v17 offset0:214 offset1:222
	ds_read2_b32 v[36:37], v17 offset0:247 offset1:255
	s_waitcnt lgkmcnt(7)
	v_bfe_u32 v19, v22, 16, 1
	s_waitcnt lgkmcnt(6)
	v_bfe_u32 v18, v24, 16, 1
	v_add3_u32 v18, v24, v18, s23
	v_lshrrev_b32_e32 v18, 16, v18
	v_add3_u32 v19, v22, v19, s23
	v_and_or_b32 v18, v19, s83, v18
	s_waitcnt lgkmcnt(5)
	v_bfe_u32 v19, v26, 16, 1
	v_add3_u32 v19, v26, v19, s23
	s_waitcnt lgkmcnt(4)
	v_bfe_u32 v20, v28, 16, 1
	v_lshrrev_b32_e32 v19, 16, v19
	v_add3_u32 v20, v28, v20, s23
	v_and_or_b32 v19, v20, s83, v19
	s_waitcnt lgkmcnt(3)
	v_bfe_u32 v20, v30, 16, 1
	v_add3_u32 v20, v30, v20, s23
	s_waitcnt lgkmcnt(2)
	v_bfe_u32 v21, v32, 16, 1
	v_lshrrev_b32_e32 v20, 16, v20
	v_add3_u32 v21, v32, v21, s23
	v_and_or_b32 v20, v21, s83, v20
	s_waitcnt lgkmcnt(1)
	v_bfe_u32 v21, v34, 16, 1
	v_add_u32_e32 v38, s4, v15
	v_add3_u32 v21, v34, v21, s23
	s_waitcnt lgkmcnt(0)
	v_bfe_u32 v22, v36, 16, 1
	v_ashrrev_i32_e32 v39, 31, v38
	v_lshrrev_b32_e32 v21, 16, v21
	v_add3_u32 v22, v36, v22, s23
	v_lshlrev_b64 v[38:39], 12, v[38:39]
	v_and_or_b32 v21, v22, s83, v21
	v_lshl_add_u64 v[38:39], v[10:11], 0, v[38:39]
	global_store_dwordx4 v[38:39], v[18:21], off nt
	v_bfe_u32 v22, v37, 16, 1
	v_add3_u32 v22, v37, v22, s23
	v_bfe_u32 v18, v25, 16, 1
	v_add3_u32 v18, v25, v18, s23
	v_bfe_u32 v19, v23, 16, 1
	v_lshrrev_b32_e32 v18, 16, v18
	v_add3_u32 v19, v23, v19, s23
	v_and_or_b32 v18, v19, s83, v18
	v_bfe_u32 v19, v27, 16, 1
	v_add3_u32 v19, v27, v19, s23
	v_bfe_u32 v20, v29, 16, 1
	v_lshrrev_b32_e32 v19, 16, v19
	v_add3_u32 v20, v29, v20, s23
	v_and_or_b32 v19, v20, s83, v19
	v_bfe_u32 v20, v31, 16, 1
	v_add3_u32 v20, v31, v20, s23
	v_bfe_u32 v21, v33, 16, 1
	v_lshrrev_b32_e32 v20, 16, v20
	v_add3_u32 v21, v33, v21, s23
	v_and_or_b32 v20, v21, s83, v20
	v_bfe_u32 v21, v35, 16, 1
	v_add3_u32 v21, v35, v21, s23
	v_lshrrev_b32_e32 v21, 16, v21
	v_and_or_b32 v21, v22, s83, v21
	v_add_u32_e32 v22, s4, v16
	v_ashrrev_i32_e32 v23, 31, v22
	v_lshlrev_b64 v[22:23], 12, v[22:23]
	v_lshl_add_u64 v[10:11], v[10:11], 0, v[22:23]
	global_store_dwordx4 v[10:11], v[18:21], off nt
	s_waitcnt lgkmcnt(0)
	s_branch .LBB0_215

.LBB0_235:
	s_cmpk_gt_u32 s8, 0x27ff
	s_cbranch_scc1 .LBB0_239
	s_add_i32 s4, s8, 0xf800
	s_bfe_u32 s4, s4, 0x80008
	s_lshl_b32 s5, s4, 6
	s_add_i32 s4, s9, s16
	s_and_b32 s4, s4, 0x1fe0
	v_add_u32_e32 v42, s5, v1
	s_lshl_b32 s88, s4, 2
	v_ashrrev_i32_e32 v43, 31, v42
	v_lshl_add_u64 v[2:3], v[34:35], 0, s[88:89]
	v_lshlrev_b64 v[4:5], 15, v[42:43]
	v_lshl_add_u64 v[26:27], v[2:3], 0, v[4:5]
	v_add_co_u32_e32 v2, vcc, 0x40000, v26
	s_nop 1
	v_addc_co_u32_e32 v3, vcc, 0, v27, vcc
	v_add_co_u32_e32 v10, vcc, 0x80000, v26
	global_load_dwordx4 v[6:9], v[26:27], off nt
	s_nop 0
	global_load_dwordx4 v[2:5], v[2:3], off nt
	v_addc_co_u32_e32 v11, vcc, 0, v27, vcc
	v_add_co_u32_e32 v12, vcc, 0xc0000, v26
	s_nop 1
	v_addc_co_u32_e32 v13, vcc, 0, v27, vcc
	v_add_co_u32_e32 v18, vcc, 0x100000, v26
	global_load_dwordx4 v[14:17], v[10:11], off nt
	s_nop 0
	global_load_dwordx4 v[10:13], v[12:13], off nt
	v_addc_co_u32_e32 v19, vcc, 0, v27, vcc
	v_add_co_u32_e32 v20, vcc, 0x140000, v26
	s_nop 1
	v_addc_co_u32_e32 v21, vcc, 0, v27, vcc
	v_add_co_u32_e32 v28, vcc, 0x180000, v26
	global_load_dwordx4 v[22:25], v[18:19], off nt
	s_nop 0
	global_load_dwordx4 v[18:21], v[20:21], off nt
	v_addc_co_u32_e32 v29, vcc, 0, v27, vcc
	v_add_co_u32_e32 v26, vcc, 0x1c0000, v26
	s_nop 1
	v_addc_co_u32_e32 v27, vcc, 0, v27, vcc
	global_load_dwordx4 v[30:33], v[28:29], off nt
	s_nop 0
	global_load_dwordx4 v[26:29], v[26:27], off nt
	s_andn2_b64 vcc, exec, s[20:21]
	s_cbranch_vccnz .LBB0_238
	v_readlane_b32 s56, v252, 23
	v_readlane_b32 s62, v252, 29
	v_readlane_b32 s63, v252, 30
	v_readlane_b32 s57, v252, 24
	v_readlane_b32 s58, v252, 25
	v_lshl_add_u64 v[42:43], v[42:43], 2, s[62:63]
	global_load_dword v52, v[42:43], off
	global_load_dword v54, v[42:43], off offset:32
	global_load_dword v56, v[42:43], off offset:64
	global_load_dword v58, v[42:43], off offset:96
	global_load_dword v60, v[42:43], off offset:128
	global_load_dword v62, v[42:43], off offset:160
	global_load_dword v64, v[42:43], off offset:192
	global_load_dword v66, v[42:43], off offset:224
	v_readlane_b32 s59, v252, 26
	v_readlane_b32 s60, v252, 27
	v_readlane_b32 s61, v252, 28
	v_readlane_b32 s64, v252, 31
	v_readlane_b32 s65, v252, 32
	v_readlane_b32 s66, v252, 33
	v_readlane_b32 s67, v252, 34
	v_readlane_b32 s68, v252, 35
	v_readlane_b32 s69, v252, 36
	v_readlane_b32 s70, v252, 37
	v_readlane_b32 s71, v252, 38
	s_waitcnt vmcnt(7)
	v_pk_mul_f32 v[8:9], v[8:9], v[52:53] op_sel_hi:[1,0]
	v_pk_mul_f32 v[6:7], v[6:7], v[52:53] op_sel_hi:[1,0]
	s_waitcnt vmcnt(6)
	v_pk_mul_f32 v[4:5], v[4:5], v[54:55] op_sel_hi:[1,0]
	v_pk_mul_f32 v[2:3], v[2:3], v[54:55] op_sel_hi:[1,0]
	s_waitcnt vmcnt(5)
	v_pk_mul_f32 v[16:17], v[16:17], v[56:57] op_sel_hi:[1,0]
	v_pk_mul_f32 v[14:15], v[14:15], v[56:57] op_sel_hi:[1,0]
	s_waitcnt vmcnt(4)
	v_pk_mul_f32 v[12:13], v[12:13], v[58:59] op_sel_hi:[1,0]
	v_pk_mul_f32 v[10:11], v[10:11], v[58:59] op_sel_hi:[1,0]
	s_waitcnt vmcnt(3)
	v_pk_mul_f32 v[24:25], v[24:25], v[60:61] op_sel_hi:[1,0]
	v_pk_mul_f32 v[22:23], v[22:23], v[60:61] op_sel_hi:[1,0]
	s_waitcnt vmcnt(2)
	v_pk_mul_f32 v[20:21], v[20:21], v[62:63] op_sel_hi:[1,0]
	v_pk_mul_f32 v[18:19], v[18:19], v[62:63] op_sel_hi:[1,0]
	s_waitcnt vmcnt(1)
	v_pk_mul_f32 v[32:33], v[32:33], v[64:65] op_sel_hi:[1,0]
	v_pk_mul_f32 v[30:31], v[30:31], v[64:65] op_sel_hi:[1,0]
	s_waitcnt vmcnt(0)
	v_pk_mul_f32 v[28:29], v[28:29], v[66:67] op_sel_hi:[1,0]
	v_pk_mul_f32 v[26:27], v[26:27], v[66:67] op_sel_hi:[1,0]

.LBB0_774:
	s_cmpk_gt_u32 s7, 0x37ff
	s_cbranch_scc1 .LBB0_778
	s_add_i32 s4, s7, 0xe000
	s_and_b32 s5, s4, 0xffff
	s_mul_i32 s5, s5, 0xaaab
	s_lshr_b32 s6, s5, 23
	s_mul_i32 s5, s6, 0xc0
	s_sub_i32 s5, s4, s5
	s_lshl_b32 s4, s6, 6
	s_lshl_b32 s6, s5, 7
	v_add_u32_e32 v42, s4, v1
	s_and_b32 s88, s6, 0x3ff80
	v_lshl_add_u64 v[2:3], v[34:35], 0, s[88:89]
	v_add_u32_e32 v6, 8, v42
	v_mad_i64_i32 v[4:5], s[16:17], v42, s91, v[2:3]
	v_mad_i64_i32 v[6:7], s[16:17], v6, s91, v[2:3]
	global_load_dwordx4 v[30:33], v[4:5], off nt
	global_load_dwordx4 v[14:17], v[6:7], off nt
	v_add_u32_e32 v4, 16, v42
	v_add_u32_e32 v6, 24, v42
	v_mad_i64_i32 v[4:5], s[16:17], v4, s91, v[2:3]
	v_mad_i64_i32 v[6:7], s[16:17], v6, s91, v[2:3]
	global_load_dwordx4 v[26:29], v[4:5], off nt
	global_load_dwordx4 v[10:13], v[6:7], off nt
	v_add_u32_e32 v4, 32, v42
	v_add_u32_e32 v6, 40, v42
	v_mad_i64_i32 v[4:5], s[16:17], v4, s91, v[2:3]
	v_mad_i64_i32 v[6:7], s[16:17], v6, s91, v[2:3]
	global_load_dwordx4 v[22:25], v[4:5], off nt
	s_nop 0
	global_load_dwordx4 v[6:9], v[6:7], off nt
	v_add_u32_e32 v4, 48, v42
	v_add_u32_e32 v18, 56, v42
	v_mad_i64_i32 v[4:5], s[16:17], v4, s91, v[2:3]
	v_mad_i64_i32 v[2:3], s[16:17], v18, s91, v[2:3]
	global_load_dwordx4 v[18:21], v[4:5], off nt
	s_nop 0
	global_load_dwordx4 v[2:5], v[2:3], off nt
	s_andn2_b64 vcc, exec, s[50:51]
	s_cbranch_vccnz .LBB0_777
	v_readlane_b32 s56, v252, 0
	v_ashrrev_i32_e32 v43, 31, v42
	v_readlane_b32 s68, v252, 12
	v_readlane_b32 s69, v252, 13
	v_readlane_b32 s57, v252, 1
	v_readlane_b32 s58, v252, 2
	v_lshl_add_u64 v[42:43], v[42:43], 2, s[68:69]
	global_load_dword v52, v[42:43], off
	global_load_dword v54, v[42:43], off offset:32
	global_load_dword v56, v[42:43], off offset:64
	global_load_dword v58, v[42:43], off offset:96
	global_load_dword v60, v[42:43], off offset:128
	global_load_dword v62, v[42:43], off offset:160
	global_load_dword v64, v[42:43], off offset:192
	global_load_dword v66, v[42:43], off offset:224
	v_readlane_b32 s59, v252, 3
	v_readlane_b32 s60, v252, 4
	v_readlane_b32 s61, v252, 5
	v_readlane_b32 s62, v252, 6
	v_readlane_b32 s63, v252, 7
	v_readlane_b32 s64, v252, 8
	v_readlane_b32 s65, v252, 9
	v_readlane_b32 s66, v252, 10
	v_readlane_b32 s67, v252, 11
	v_readlane_b32 s70, v252, 14
	v_readlane_b32 s71, v252, 15
	s_waitcnt vmcnt(7)
	v_pk_mul_f32 v[32:33], v[32:33], v[52:53] op_sel_hi:[1,0]
	v_pk_mul_f32 v[30:31], v[30:31], v[52:53] op_sel_hi:[1,0]
	s_waitcnt vmcnt(6)
	v_pk_mul_f32 v[16:17], v[16:17], v[54:55] op_sel_hi:[1,0]
	v_pk_mul_f32 v[14:15], v[14:15], v[54:55] op_sel_hi:[1,0]
	s_waitcnt vmcnt(5)
	v_pk_mul_f32 v[28:29], v[28:29], v[56:57] op_sel_hi:[1,0]
	v_pk_mul_f32 v[26:27], v[26:27], v[56:57] op_sel_hi:[1,0]
	s_waitcnt vmcnt(4)
	v_pk_mul_f32 v[12:13], v[12:13], v[58:59] op_sel_hi:[1,0]
	v_pk_mul_f32 v[10:11], v[10:11], v[58:59] op_sel_hi:[1,0]
	s_waitcnt vmcnt(3)
	v_pk_mul_f32 v[24:25], v[24:25], v[60:61] op_sel_hi:[1,0]
	v_pk_mul_f32 v[22:23], v[22:23], v[60:61] op_sel_hi:[1,0]
	s_waitcnt vmcnt(2)
	v_pk_mul_f32 v[8:9], v[8:9], v[62:63] op_sel_hi:[1,0]
	v_pk_mul_f32 v[6:7], v[6:7], v[62:63] op_sel_hi:[1,0]
	s_waitcnt vmcnt(1)
	v_pk_mul_f32 v[20:21], v[20:21], v[64:65] op_sel_hi:[1,0]
	v_pk_mul_f32 v[18:19], v[18:19], v[64:65] op_sel_hi:[1,0]
	s_waitcnt vmcnt(0)
	v_pk_mul_f32 v[4:5], v[4:5], v[66:67] op_sel_hi:[1,0]
	v_pk_mul_f32 v[2:3], v[2:3], v[66:67] op_sel_hi:[1,0]
